# v36 + tighter grid-barrier spin: s_sleep 1 -> s_sleep 0 in the arrival / generation poll loops
# baseline (speedup 1.0000x reference)
; DI unsigned xb_ld(unsigned* p) { return __hip_atomic_load(p, __ATOMIC_RELAXED, __HIP_MEMORY_SCOPE_AGENT); }
; DI void xcd_barrier_complete(unsigned* bar, unsigned x, unsigned& nloc, unsigned& nx) {
;     ...
;   for (;;) {
;     sum = 0u; cnt = 0u; mine = 0u;
; #pragma unroll
;     for (unsigned j = 0; j < 16; ++j) { const unsigned c = xb_ld(&bar[XB_XCNT(j)]); sum += c; cnt += (c > 0u) ? 1u : 0u; mine = (j == x) ? c : mine; }
;     if (sum == G) break;
;     __builtin_amdgcn_s_sleep(1);
;     if ((++sp & 255u) == 0u) { if (xb_ld(&bar[XB_TMO])) break; if (sp > XB_SPIN_CAP) { atomicAdd(&bar[XB_TMO], 1u); break; } }
;   }
.LBB0_17:
	global_load_dword v24, v[188:189], off offset:1024 sc1
	global_load_dword v22, v[188:189], off offset:1280 sc1
	global_load_dword v23, v[188:189], off offset:1536 sc1
	global_load_dword v20, v[188:189], off offset:1792 sc1
	global_load_dword v21, v[188:189], off offset:2048 sc1
	global_load_dword v18, v[188:189], off offset:2304 sc1
	global_load_dword v19, v[188:189], off offset:2560 sc1
	global_load_dword v16, v[188:189], off offset:2816 sc1
	global_load_dword v17, v[188:189], off offset:3072 sc1
	global_load_dword v14, v[188:189], off offset:3328 sc1
	global_load_dword v15, v[188:189], off offset:3584 sc1
	global_load_dword v12, v[188:189], off offset:3840 sc1
	global_load_dword v13, v[2:3], off sc1
	global_load_dword v10, v[4:5], off sc1
	global_load_dword v11, v[6:7], off sc1
	global_load_dword v1, v[8:9], off sc1
	s_or_b64 s[10:11], s[10:11], exec
	s_or_b64 s[8:9], s[8:9], exec
	s_waitcnt vmcnt(14)
	v_add_u32_e32 v25, v22, v24
	s_waitcnt vmcnt(12)
	v_add3_u32 v25, v25, v23, v20
	s_waitcnt vmcnt(10)
	v_add3_u32 v25, v25, v21, v18
	s_waitcnt vmcnt(8)
	v_add3_u32 v25, v25, v19, v16
	s_waitcnt vmcnt(6)
	v_add3_u32 v25, v25, v17, v14
	s_waitcnt vmcnt(4)
	v_add3_u32 v25, v25, v15, v12
	s_waitcnt vmcnt(2)
	v_add3_u32 v25, v25, v13, v10
	s_waitcnt vmcnt(0)
	v_add3_u32 v25, v25, v11, v1
	v_cmp_ne_u32_e32 vcc, s13, v25
	s_and_saveexec_b64 s[14:15], vcc
	s_cbranch_execz .LBB0_16
	s_and_b32 s18, s24, 0xff
	s_mov_b64 s[16:17], -1
	s_cmp_eq_u32 s18, 0
	s_mov_b64 s[20:21], -1
	s_mov_b64 s[18:19], -1
	s_sleep 0
	s_cbranch_scc1 .LBB0_20
	s_and_saveexec_b64 s[22:23], s[20:21]
	s_cbranch_execz .LBB0_15
	s_branch .LBB0_23

.LBB0_38:
	s_and_b32 s16, s24, 0xff
	s_cmp_lg_u32 s16, 0
	s_mov_b64 s[18:19], -1
	s_sleep 0
	s_cbranch_scc0 .LBB0_40
	s_mov_b64 s[20:21], -1
	s_and_saveexec_b64 s[22:23], s[18:19]
	s_cbranch_execz .LBB0_37
	s_branch .LBB0_43

; DI unsigned xb_ld(unsigned* p) { return __hip_atomic_load(p, __ATOMIC_RELAXED, __HIP_MEMORY_SCOPE_AGENT); }
; DI void xcd_barrier_complete(unsigned* bar, unsigned x, unsigned& nloc, unsigned& nx) {
;     ...
;   for (;;) {
;     sum = 0u; cnt = 0u; mine = 0u;
; #pragma unroll
;     for (unsigned j = 0; j < 16; ++j) { const unsigned c = xb_ld(&bar[XB_XCNT(j)]); sum += c; cnt += (c > 0u) ? 1u : 0u; mine = (j == x) ? c : mine; }
;     if (sum == G) break;
;     __builtin_amdgcn_s_sleep(1);
;     if ((++sp & 255u) == 0u) { if (xb_ld(&bar[XB_TMO])) break; if (sp > XB_SPIN_CAP) { atomicAdd(&bar[XB_TMO], 1u); break; } }
;   }
.LBB0_999:
	global_load_dword v24, v[188:189], off offset:1024 sc1
	global_load_dword v22, v[188:189], off offset:1280 sc1
	global_load_dword v23, v[188:189], off offset:1536 sc1
	global_load_dword v20, v[188:189], off offset:1792 sc1
	global_load_dword v21, v[188:189], off offset:2048 sc1
	global_load_dword v18, v[188:189], off offset:2304 sc1
	global_load_dword v19, v[188:189], off offset:2560 sc1
	global_load_dword v16, v[188:189], off offset:2816 sc1
	global_load_dword v17, v[188:189], off offset:3072 sc1
	global_load_dword v14, v[188:189], off offset:3328 sc1
	global_load_dword v15, v[188:189], off offset:3584 sc1
	global_load_dword v12, v[188:189], off offset:3840 sc1
	global_load_dword v13, v[2:3], off sc1
	global_load_dword v10, v[4:5], off sc1
	global_load_dword v11, v[6:7], off sc1
	global_load_dword v1, v[8:9], off sc1
	s_or_b64 s[8:9], s[8:9], exec
	s_or_b64 s[6:7], s[6:7], exec
	s_waitcnt vmcnt(14)
	v_add_u32_e32 v25, v22, v24
	s_waitcnt vmcnt(12)
	v_add3_u32 v25, v25, v23, v20
	s_waitcnt vmcnt(10)
	v_add3_u32 v25, v25, v21, v18
	s_waitcnt vmcnt(8)
	v_add3_u32 v25, v25, v19, v16
	s_waitcnt vmcnt(6)
	v_add3_u32 v25, v25, v17, v14
	s_waitcnt vmcnt(4)
	v_add3_u32 v25, v25, v15, v12
	s_waitcnt vmcnt(2)
	v_add3_u32 v25, v25, v13, v10
	s_waitcnt vmcnt(0)
	v_add3_u32 v25, v25, v11, v1
	v_cmp_ne_u32_e32 vcc, s13, v25
	s_and_saveexec_b64 s[10:11], vcc
	s_cbranch_execz .LBB0_998
	s_and_b32 s16, s22, 0xff
	s_mov_b64 s[14:15], -1
	s_cmp_eq_u32 s16, 0
	s_mov_b64 s[18:19], -1
	s_mov_b64 s[16:17], -1
	s_sleep 0
	s_cbranch_scc1 .LBB0_1002
	s_and_saveexec_b64 s[20:21], s[18:19]
	s_cbranch_execz .LBB0_997
	s_branch .LBB0_1005

.LBB0_1017:
	s_and_b32 s16, s22, 0xff
	s_mov_b64 s[14:15], -1
	s_cmp_lg_u32 s16, 0
	s_mov_b64 s[16:17], -1
	s_sleep 0
	s_cbranch_scc1 .LBB0_1021
	global_load_dword v4, v[188:189], off offset:512 sc1
	s_mov_b64 s[16:17], 0
	s_mov_b64 s[18:19], -1
	s_waitcnt vmcnt(0)
	v_cmp_eq_u32_e32 vcc, 0, v4
	s_and_saveexec_b64 s[20:21], vcc
	s_cmp_lt_u32 s22, 0x400001
	s_cselect_b64 s[16:17], -1, 0
	s_xor_b64 s[18:19], exec, -1
	s_and_b64 s[16:17], s[16:17], exec
	s_or_b64 exec, exec, s[20:21]

.LBB0_1034:
	s_and_b32 s10, s20, 0xff
	s_cmp_lg_u32 s10, 0
	s_mov_b64 s[14:15], -1
	s_sleep 0
	s_cbranch_scc0 .LBB0_1036
	s_mov_b64 s[16:17], -1
	s_and_saveexec_b64 s[18:19], s[14:15]
	s_cbranch_execz .LBB0_1033
	s_branch .LBB0_1039
